# cache policy: sc1 (write-through, not retained in the writer's L2) on the gate-up epilogue's ACT stores (write-once, read by the next phase on other CUs), on top of the nt streams
# speedup vs baseline: 1.0170x; 1.0014x over previous
; __device__ __forceinline__ unsigned cvt_pk(float lo, float hi) { unsigned r; asm("v_cvt_pk_bf16_f32 %0, %1, %2" : "=v"(r) : "v"(lo), "v"(hi)); return r; }
; __device__ __forceinline__ float fexp2(float x) { return __builtin_amdgcn_exp2f(x); }
; __device__ __forceinline__ float frcp(float x) { return __builtin_amdgcn_rcpf(x); }
;     __device__ __forceinline__ void operator()(AccRef acc, const pg8::Unit& u, int wr, int wc, int, int) const {
;     ...
;         bf16* ACT = (bf16*)(ws + WS_ACT); const float* ssq = (const float*)(ws + WS_SSQ) + ssq_off;
;         float sq[2][4];
; #pragma unroll
;         for (int ai = 0; ai < 2; ++ai)
; #pragma unroll
;             for (int m = 0; m < 4; ++m) sq[ai][m] = ssq[u.pm * 256 + ai * 128 + wr * 64 + m * 16 + fr];
;         asm volatile("" ::: "memory");
; #pragma unroll
;         for (int ai = 0; ai < 2; ++ai)
; #pragma unroll
;             for (int m = 0; m < 4; ++m) {
;                 const int row = u.pm * 256 + ai * 128 + wr * 64 + m * 16 + fr;
;                 const float rstd = __builtin_amdgcn_rsqf(sq[ai][m] * (1.0f / DM) + EPS);
;                 const float rc = -rstd * LOG2E, r2 = rstd * rstd;
;                 unsigned pk[4];
; #pragma unroll
;                 for (int n = 0; n < 2; ++n)
; #pragma unroll
;                     for (int h = 0; h < 2; ++h) {
;                         const f32x2 g2 = {acc[ai][0][m][n][2 * h], acc[ai][0][m][n][2 * h + 1]}, u2 = {acc[ai][1][m][n][2 * h], acc[ai][1][m][n][2 * h + 1]};
;                         const f32x2 x2 = g2 * rc; f32x2 d2; d2.x = fexp2(x2.x); d2.y = fexp2(x2.y); d2 = d2 + 1.0f;
;                         f32x2 q2; q2.x = frcp(d2.x); q2.y = frcp(d2.y);
;                         const f32x2 t2 = (g2 * u2) * r2 * q2;
;                         pk[2 * n + h] = cvt_pk(t2.x, t2.y);
;                     }
;                 v4u w; w.x = pk[0]; w.y = pk[1]; w.z = pk[2]; w.w = pk[3];
;                 *(v4u*)(ACT + (size_t)row * FF + u.pn * 128 + wc * 32 + 8 * fq) = w;
.LBB0_612:
	s_mov_b64 s[36:37], s[44:45]
	s_mov_b64 s[38:39], s[46:47]
	s_add_u32 s38, s36, 0x22000
	s_addc_u32 s39, s37, 0
	s_lshl_b32 s15, s58, 8
	v_mov_b32_e32 v158, v196
	s_add_i32 s15, s15, s35
	v_pk_mul_f32 v[120:121], v[124:125], v[120:121]
	v_and_or_b32 v156, v158, 15, s15
	v_ashrrev_i32_e32 v157, 31, v156
	v_lshl_add_u64 v[140:141], v[156:157], 2, s[38:39]
	global_load_dword v157, v[140:141], off
	v_or_b32_e32 v154, 16, v156
	v_ashrrev_i32_e32 v155, 31, v154
	v_lshl_add_u64 v[140:141], v[154:155], 2, s[38:39]
	global_load_dword v155, v[140:141], off
	v_or_b32_e32 v152, 32, v156
	v_ashrrev_i32_e32 v153, 31, v152
	v_lshl_add_u64 v[140:141], v[152:153], 2, s[38:39]
	global_load_dword v153, v[140:141], off
	v_or_b32_e32 v150, 48, v156
	v_ashrrev_i32_e32 v151, 31, v150
	v_add_u32_e32 v148, 0x80, v156
	v_lshl_add_u64 v[140:141], v[150:151], 2, s[38:39]
	v_ashrrev_i32_e32 v149, 31, v148
	v_add_u32_e32 v146, 0x90, v156
	global_load_dword v151, v[140:141], off
	v_lshl_add_u64 v[140:141], v[148:149], 2, s[38:39]
	v_ashrrev_i32_e32 v147, 31, v146
	v_add_u32_e32 v144, 0xa0, v156
	global_load_dword v149, v[140:141], off
	v_lshl_add_u64 v[140:141], v[146:147], 2, s[38:39]
	v_ashrrev_i32_e32 v145, 31, v144
	global_load_dword v147, v[140:141], off
	v_lshl_add_u64 v[140:141], v[144:145], 2, s[38:39]
	global_load_dword v145, v[140:141], off
	v_add_u32_e32 v140, 0xb0, v156
	v_ashrrev_i32_e32 v141, 31, v140
	v_lshl_add_u64 v[142:143], v[140:141], 2, s[38:39]
	global_load_dword v141, v[142:143], off
	v_ashrrev_i32_e32 v142, 1, v158
	v_pk_mul_f32 v[122:123], v[126:127], v[122:123]
	v_pk_mul_f32 v[112:113], v[116:117], v[112:113]
	s_lshl_b32 s38, s56, 7
	s_ashr_i32 s39, s38, 31
	s_lshl_b64 s[38:39], s[38:39], 1
	s_add_u32 s15, s36, s38
	s_addc_u32 s31, s37, s39
	s_add_u32 s36, s15, s71
	v_and_b32_e32 v142, -8, v142
	s_addc_u32 s37, s31, 0
	v_ashrrev_i32_e32 v143, 31, v142
	v_pk_mul_f32 v[114:115], v[118:119], v[114:115]
	v_lshl_add_u64 v[142:143], v[142:143], 1, s[36:37]
	s_mov_b64 s[36:37], 0xba00000
	v_lshl_add_u64 v[142:143], v[142:143], 0, s[36:37]
	v_pk_mul_f32 v[104:105], v[108:109], v[104:105]
	v_pk_mul_f32 v[106:107], v[110:111], v[106:107]
	v_pk_mul_f32 v[96:97], v[100:101], v[96:97]
	v_pk_mul_f32 v[98:99], v[102:103], v[98:99]
	v_pk_mul_f32 v[88:89], v[92:93], v[88:89]
	v_pk_mul_f32 v[90:91], v[94:95], v[90:91]
	v_pk_mul_f32 v[80:81], v[84:85], v[80:81]
	v_pk_mul_f32 v[82:83], v[86:87], v[82:83]
	v_pk_mul_f32 v[72:73], v[76:77], v[72:73]
	v_pk_mul_f32 v[74:75], v[78:79], v[74:75]
	v_pk_mul_f32 v[64:65], v[68:69], v[64:65]
	v_pk_mul_f32 v[66:67], v[70:71], v[66:67]
	v_pk_mul_f32 v[56:57], v[60:61], v[56:57]
	v_pk_mul_f32 v[58:59], v[62:63], v[58:59]
	v_pk_mul_f32 v[48:49], v[52:53], v[48:49]
	v_pk_mul_f32 v[50:51], v[54:55], v[50:51]
	v_pk_mul_f32 v[40:41], v[44:45], v[40:41]
	v_pk_mul_f32 v[42:43], v[46:47], v[42:43]
	v_pk_mul_f32 v[32:33], v[36:37], v[32:33]
	v_pk_mul_f32 v[34:35], v[38:39], v[34:35]
	v_pk_mul_f32 v[24:25], v[28:29], v[24:25]
	v_pk_mul_f32 v[26:27], v[30:31], v[26:27]
	v_pk_mul_f32 v[16:17], v[20:21], v[16:17]
	v_pk_mul_f32 v[18:19], v[22:23], v[18:19]
	v_pk_mul_f32 v[8:9], v[12:13], v[8:9]
	v_pk_mul_f32 v[10:11], v[14:15], v[10:11]
	v_pk_mul_f32 v[0:1], v[4:5], v[0:1]
	v_pk_mul_f32 v[2:3], v[6:7], v[2:3]
	s_mov_b64 s[56:57], -1
	s_andn2_b64 vcc, exec, s[42:43]
	s_waitcnt vmcnt(0)
	v_fmamk_f32 v157, v157, 0x3a800000, v165
	v_rsq_f32_e32 v157, v157
	s_nop 0
	v_mul_f32_e32 v160, 0xbfb8aa3b, v157
	v_pk_mul_f32 v[166:167], v[124:125], v[160:161] op_sel_hi:[1,0]
	v_pk_mul_f32 v[124:125], v[126:127], v[160:161] op_sel_hi:[1,0]
	v_exp_f32_e32 v166, v166
	v_exp_f32_e32 v167, v167
	v_exp_f32_e32 v124, v124
	v_exp_f32_e32 v125, v125
	v_mul_f32_e32 v158, v157, v157
	v_pk_add_f32 v[166:167], v[166:167], 1.0 op_sel_hi:[1,0]
	v_pk_mul_f32 v[120:121], v[120:121], v[158:159] op_sel_hi:[1,0]
	v_pk_add_f32 v[124:125], v[124:125], 1.0 op_sel_hi:[1,0]
	v_rcp_f32_e32 v166, v166
	v_rcp_f32_e32 v167, v167
	v_rcp_f32_e32 v124, v124
	v_rcp_f32_e32 v125, v125
	v_pk_mul_f32 v[122:123], v[122:123], v[158:159] op_sel_hi:[1,0]
	v_pk_mul_f32 v[120:121], v[120:121], v[166:167]
	v_pk_mul_f32 v[112:113], v[112:113], v[158:159] op_sel_hi:[1,0]
	v_pk_mul_f32 v[122:123], v[122:123], v[124:125]
	v_cvt_pk_bf16_f32 v120, v120, v121
	v_pk_mul_f32 v[114:115], v[114:115], v[158:159] op_sel_hi:[1,0]
	v_cvt_pk_bf16_f32 v121, v122, v123
	v_pk_mul_f32 v[122:123], v[116:117], v[160:161] op_sel_hi:[1,0]
	s_nop 0
	v_exp_f32_e32 v122, v122
	v_exp_f32_e32 v123, v123
	s_nop 0
	v_pk_add_f32 v[122:123], v[122:123], 1.0 op_sel_hi:[1,0]
	s_nop 0
	v_rcp_f32_e32 v122, v122
	v_rcp_f32_e32 v123, v123
	s_nop 0
	v_pk_mul_f32 v[112:113], v[112:113], v[122:123]
	s_nop 0
	v_cvt_pk_bf16_f32 v122, v112, v113
	v_pk_mul_f32 v[112:113], v[118:119], v[160:161] op_sel_hi:[1,0]
	s_nop 0
	v_exp_f32_e32 v112, v112
	v_exp_f32_e32 v113, v113
	s_nop 0
	v_pk_add_f32 v[112:113], v[112:113], 1.0 op_sel_hi:[1,0]
	s_nop 0
	v_rcp_f32_e32 v112, v112
	v_rcp_f32_e32 v113, v113
	s_nop 0
	v_pk_mul_f32 v[112:113], v[114:115], v[112:113]
	s_nop 0
	v_cvt_pk_bf16_f32 v123, v112, v113
	v_mad_i64_i32 v[112:113], s[36:37], v156, s74, v[142:143]
	global_store_dwordx4 v[112:113], v[120:123], off sc1
	v_fmamk_f32 v112, v155, 0x3a800000, v165
	v_rsq_f32_e32 v112, v112
	s_nop 0
	v_mul_f32_e32 v114, 0xbfb8aa3b, v112
	v_pk_mul_f32 v[116:117], v[108:109], v[114:115] op_sel_hi:[1,0]
	v_pk_mul_f32 v[108:109], v[110:111], v[114:115] op_sel_hi:[1,0]
	v_exp_f32_e32 v116, v116
	v_exp_f32_e32 v117, v117
	v_exp_f32_e32 v108, v108
	v_exp_f32_e32 v109, v109
	v_mul_f32_e32 v112, v112, v112
	v_pk_add_f32 v[116:117], v[116:117], 1.0 op_sel_hi:[1,0]
; __device__ __forceinline__ unsigned cvt_pk(float lo, float hi) { unsigned r; asm("v_cvt_pk_bf16_f32 %0, %1, %2" : "=v"(r) : "v"(lo), "v"(hi)); return r; }
; __device__ __forceinline__ float fexp2(float x) { return __builtin_amdgcn_exp2f(x); }
; __device__ __forceinline__ float frcp(float x) { return __builtin_amdgcn_rcpf(x); }
;     __device__ __forceinline__ void operator()(AccRef acc, const pg8::Unit& u, int wr, int wc, int, int) const {
;     ...
;         for (int ai = 0; ai < 2; ++ai)
; #pragma unroll
;             for (int m = 0; m < 4; ++m) {
;                 const int row = u.pm * 256 + ai * 128 + wr * 64 + m * 16 + fr;
;                 const float rstd = __builtin_amdgcn_rsqf(sq[ai][m] * (1.0f / DM) + EPS);
;                 const float rc = -rstd * LOG2E, r2 = rstd * rstd;
;                 unsigned pk[4];
; #pragma unroll
;                 for (int n = 0; n < 2; ++n)
; #pragma unroll
;                     for (int h = 0; h < 2; ++h) {
;                         const f32x2 g2 = {acc[ai][0][m][n][2 * h], acc[ai][0][m][n][2 * h + 1]}, u2 = {acc[ai][1][m][n][2 * h], acc[ai][1][m][n][2 * h + 1]};
;                         const f32x2 x2 = g2 * rc; f32x2 d2; d2.x = fexp2(x2.x); d2.y = fexp2(x2.y); d2 = d2 + 1.0f;
;                         f32x2 q2; q2.x = frcp(d2.x); q2.y = frcp(d2.y);
;                         const f32x2 t2 = (g2 * u2) * r2 * q2;
;                         pk[2 * n + h] = cvt_pk(t2.x, t2.y);
;                     }
;                 v4u w; w.x = pk[0]; w.y = pk[1]; w.z = pk[2]; w.w = pk[3];
;                 *(v4u*)(ACT + (size_t)row * FF + u.pn * 128 + wc * 32 + 8 * fq) = w;
	v_pk_mul_f32 v[104:105], v[104:105], v[112:113] op_sel_hi:[1,0]
	v_pk_add_f32 v[108:109], v[108:109], 1.0 op_sel_hi:[1,0]
	v_rcp_f32_e32 v116, v116
	v_rcp_f32_e32 v117, v117
	v_rcp_f32_e32 v108, v108
	v_rcp_f32_e32 v109, v109
	v_pk_mul_f32 v[106:107], v[106:107], v[112:113] op_sel_hi:[1,0]
	v_pk_mul_f32 v[104:105], v[104:105], v[116:117]
	v_pk_mul_f32 v[96:97], v[96:97], v[112:113] op_sel_hi:[1,0]
	v_pk_mul_f32 v[106:107], v[106:107], v[108:109]
	v_cvt_pk_bf16_f32 v104, v104, v105
	v_pk_mul_f32 v[98:99], v[98:99], v[112:113] op_sel_hi:[1,0]
	v_cvt_pk_bf16_f32 v105, v106, v107
	v_pk_mul_f32 v[106:107], v[100:101], v[114:115] op_sel_hi:[1,0]
	s_nop 0
	v_exp_f32_e32 v106, v106
	v_exp_f32_e32 v107, v107
	s_nop 0
	v_pk_add_f32 v[106:107], v[106:107], 1.0 op_sel_hi:[1,0]
	s_nop 0
	v_rcp_f32_e32 v106, v106
	v_rcp_f32_e32 v107, v107
	s_nop 0
	v_pk_mul_f32 v[96:97], v[96:97], v[106:107]
	s_nop 0
	v_cvt_pk_bf16_f32 v106, v96, v97
	v_pk_mul_f32 v[96:97], v[102:103], v[114:115] op_sel_hi:[1,0]
	s_nop 0
	v_exp_f32_e32 v96, v96
	v_exp_f32_e32 v97, v97
	s_nop 0
	v_pk_add_f32 v[96:97], v[96:97], 1.0 op_sel_hi:[1,0]
	s_nop 0
	v_rcp_f32_e32 v96, v96
	v_rcp_f32_e32 v97, v97
	s_nop 0
	v_pk_mul_f32 v[96:97], v[98:99], v[96:97]
	s_nop 0
	v_cvt_pk_bf16_f32 v107, v96, v97
	v_mad_i64_i32 v[96:97], s[36:37], v154, s74, v[142:143]
	global_store_dwordx4 v[96:97], v[104:107], off sc1
	v_fmamk_f32 v96, v153, 0x3a800000, v165
	v_rsq_f32_e32 v97, v96
	s_nop 0
	v_mul_f32_e32 v96, 0xbfb8aa3b, v97
	v_pk_mul_f32 v[100:101], v[92:93], v[96:97] op_sel_hi:[1,0]
	v_pk_mul_f32 v[92:93], v[94:95], v[96:97] op_sel_hi:[1,0]
	v_exp_f32_e32 v100, v100
	v_exp_f32_e32 v101, v101
	v_exp_f32_e32 v92, v92
	v_exp_f32_e32 v93, v93
	v_mul_f32_e32 v98, v97, v97
	v_pk_add_f32 v[100:101], v[100:101], 1.0 op_sel_hi:[1,0]
	v_pk_mul_f32 v[88:89], v[88:89], v[98:99] op_sel_hi:[1,0]
	v_pk_add_f32 v[92:93], v[92:93], 1.0 op_sel_hi:[1,0]
	v_rcp_f32_e32 v100, v100
	v_rcp_f32_e32 v101, v101
	v_rcp_f32_e32 v92, v92
	v_rcp_f32_e32 v93, v93
	v_pk_mul_f32 v[90:91], v[90:91], v[98:99] op_sel_hi:[1,0]
	v_pk_mul_f32 v[88:89], v[88:89], v[100:101]
	v_pk_mul_f32 v[80:81], v[80:81], v[98:99] op_sel_hi:[1,0]
	v_pk_mul_f32 v[90:91], v[90:91], v[92:93]
	v_cvt_pk_bf16_f32 v88, v88, v89
	v_pk_mul_f32 v[82:83], v[82:83], v[98:99] op_sel_hi:[1,0]
	v_cvt_pk_bf16_f32 v89, v90, v91
	v_pk_mul_f32 v[90:91], v[84:85], v[96:97] op_sel_hi:[1,0]
	s_nop 0
	v_exp_f32_e32 v90, v90
	v_exp_f32_e32 v91, v91
	s_nop 0
	v_pk_add_f32 v[90:91], v[90:91], 1.0 op_sel_hi:[1,0]
	s_nop 0
	v_rcp_f32_e32 v90, v90
	v_rcp_f32_e32 v91, v91
	s_nop 0
	v_pk_mul_f32 v[80:81], v[80:81], v[90:91]
	s_nop 0
	v_cvt_pk_bf16_f32 v90, v80, v81
	v_pk_mul_f32 v[80:81], v[86:87], v[96:97] op_sel_hi:[1,0]
	s_nop 0
	v_exp_f32_e32 v80, v80
	v_exp_f32_e32 v81, v81
	s_nop 0
	v_pk_add_f32 v[80:81], v[80:81], 1.0 op_sel_hi:[1,0]
	s_nop 0
	v_rcp_f32_e32 v80, v80
	v_rcp_f32_e32 v81, v81
	s_nop 0
	v_pk_mul_f32 v[80:81], v[82:83], v[80:81]
	s_nop 0
	v_cvt_pk_bf16_f32 v91, v80, v81
	v_mad_i64_i32 v[80:81], s[36:37], v152, s74, v[142:143]
	global_store_dwordx4 v[80:81], v[88:91], off sc1
	v_fmamk_f32 v80, v151, 0x3a800000, v165
	v_rsq_f32_e32 v81, v80
	s_nop 0
	v_mul_f32_e32 v80, 0xbfb8aa3b, v81
	v_pk_mul_f32 v[84:85], v[76:77], v[80:81] op_sel_hi:[1,0]
	v_pk_mul_f32 v[76:77], v[78:79], v[80:81] op_sel_hi:[1,0]
	v_exp_f32_e32 v84, v84
	v_exp_f32_e32 v85, v85
	v_exp_f32_e32 v76, v76
	v_exp_f32_e32 v77, v77
	v_mul_f32_e32 v82, v81, v81
	v_pk_add_f32 v[84:85], v[84:85], 1.0 op_sel_hi:[1,0]
	v_pk_mul_f32 v[72:73], v[72:73], v[82:83] op_sel_hi:[1,0]
	v_pk_add_f32 v[76:77], v[76:77], 1.0 op_sel_hi:[1,0]
	v_rcp_f32_e32 v84, v84
	v_rcp_f32_e32 v85, v85
	v_rcp_f32_e32 v76, v76
	v_rcp_f32_e32 v77, v77
	v_pk_mul_f32 v[74:75], v[74:75], v[82:83] op_sel_hi:[1,0]
	v_pk_mul_f32 v[72:73], v[72:73], v[84:85]
	v_pk_mul_f32 v[64:65], v[64:65], v[82:83] op_sel_hi:[1,0]
	v_pk_mul_f32 v[74:75], v[74:75], v[76:77]
	v_cvt_pk_bf16_f32 v72, v72, v73
	v_pk_mul_f32 v[66:67], v[66:67], v[82:83] op_sel_hi:[1,0]
	v_cvt_pk_bf16_f32 v73, v74, v75
	v_pk_mul_f32 v[74:75], v[68:69], v[80:81] op_sel_hi:[1,0]
	s_nop 0
	v_exp_f32_e32 v74, v74
	v_exp_f32_e32 v75, v75
	s_nop 0
	v_pk_add_f32 v[74:75], v[74:75], 1.0 op_sel_hi:[1,0]
	s_nop 0
	v_rcp_f32_e32 v74, v74
	v_rcp_f32_e32 v75, v75
	s_nop 0
	v_pk_mul_f32 v[64:65], v[64:65], v[74:75]
	s_nop 0
	v_cvt_pk_bf16_f32 v74, v64, v65
	v_pk_mul_f32 v[64:65], v[70:71], v[80:81] op_sel_hi:[1,0]
	s_nop 0
	v_exp_f32_e32 v64, v64
	v_exp_f32_e32 v65, v65
	s_nop 0
	v_pk_add_f32 v[64:65], v[64:65], 1.0 op_sel_hi:[1,0]
	s_nop 0
	v_rcp_f32_e32 v64, v64
	v_rcp_f32_e32 v65, v65
	s_nop 0
	v_pk_mul_f32 v[64:65], v[66:67], v[64:65]
	s_nop 0
	v_cvt_pk_bf16_f32 v75, v64, v65
	v_mad_i64_i32 v[64:65], s[36:37], v150, s74, v[142:143]
	global_store_dwordx4 v[64:65], v[72:75], off sc1
	v_fmamk_f32 v64, v149, 0x3a800000, v165
	v_rsq_f32_e32 v65, v64
	s_nop 0
	v_mul_f32_e32 v64, 0xbfb8aa3b, v65
	v_pk_mul_f32 v[68:69], v[60:61], v[64:65] op_sel_hi:[1,0]
	v_pk_mul_f32 v[60:61], v[62:63], v[64:65] op_sel_hi:[1,0]
	v_exp_f32_e32 v68, v68
	v_exp_f32_e32 v69, v69
	v_exp_f32_e32 v60, v60
	v_exp_f32_e32 v61, v61
	v_mul_f32_e32 v66, v65, v65
	v_pk_add_f32 v[68:69], v[68:69], 1.0 op_sel_hi:[1,0]
	v_pk_mul_f32 v[56:57], v[56:57], v[66:67] op_sel_hi:[1,0]
	v_pk_add_f32 v[60:61], v[60:61], 1.0 op_sel_hi:[1,0]
	v_rcp_f32_e32 v68, v68
	v_rcp_f32_e32 v69, v69
	v_rcp_f32_e32 v60, v60
	v_rcp_f32_e32 v61, v61
	v_pk_mul_f32 v[58:59], v[58:59], v[66:67] op_sel_hi:[1,0]
	v_pk_mul_f32 v[56:57], v[56:57], v[68:69]
	v_pk_mul_f32 v[48:49], v[48:49], v[66:67] op_sel_hi:[1,0]
	v_pk_mul_f32 v[58:59], v[58:59], v[60:61]
; __device__ __forceinline__ unsigned cvt_pk(float lo, float hi) { unsigned r; asm("v_cvt_pk_bf16_f32 %0, %1, %2" : "=v"(r) : "v"(lo), "v"(hi)); return r; }
; __device__ __forceinline__ float fexp2(float x) { return __builtin_amdgcn_exp2f(x); }
; __device__ __forceinline__ float frcp(float x) { return __builtin_amdgcn_rcpf(x); }
;     __device__ __forceinline__ void operator()(AccRef acc, const pg8::Unit& u, int wr, int wc, int, int) const {
;     ...
;         for (int ai = 0; ai < 2; ++ai)
; #pragma unroll
;             for (int m = 0; m < 4; ++m) {
;                 const int row = u.pm * 256 + ai * 128 + wr * 64 + m * 16 + fr;
;                 const float rstd = __builtin_amdgcn_rsqf(sq[ai][m] * (1.0f / DM) + EPS);
;                 const float rc = -rstd * LOG2E, r2 = rstd * rstd;
;                 unsigned pk[4];
; #pragma unroll
;                 for (int n = 0; n < 2; ++n)
; #pragma unroll
;                     for (int h = 0; h < 2; ++h) {
;                         const f32x2 g2 = {acc[ai][0][m][n][2 * h], acc[ai][0][m][n][2 * h + 1]}, u2 = {acc[ai][1][m][n][2 * h], acc[ai][1][m][n][2 * h + 1]};
;                         const f32x2 x2 = g2 * rc; f32x2 d2; d2.x = fexp2(x2.x); d2.y = fexp2(x2.y); d2 = d2 + 1.0f;
;                         f32x2 q2; q2.x = frcp(d2.x); q2.y = frcp(d2.y);
;                         const f32x2 t2 = (g2 * u2) * r2 * q2;
;                         pk[2 * n + h] = cvt_pk(t2.x, t2.y);
;                     }
;                 v4u w; w.x = pk[0]; w.y = pk[1]; w.z = pk[2]; w.w = pk[3];
;                 *(v4u*)(ACT + (size_t)row * FF + u.pn * 128 + wc * 32 + 8 * fq) = w;
	v_cvt_pk_bf16_f32 v56, v56, v57
	v_pk_mul_f32 v[50:51], v[50:51], v[66:67] op_sel_hi:[1,0]
	v_cvt_pk_bf16_f32 v57, v58, v59
	v_pk_mul_f32 v[58:59], v[52:53], v[64:65] op_sel_hi:[1,0]
	s_nop 0
	v_exp_f32_e32 v58, v58
	v_exp_f32_e32 v59, v59
	s_nop 0
	v_pk_add_f32 v[58:59], v[58:59], 1.0 op_sel_hi:[1,0]
	s_nop 0
	v_rcp_f32_e32 v58, v58
	v_rcp_f32_e32 v59, v59
	s_nop 0
	v_pk_mul_f32 v[48:49], v[48:49], v[58:59]
	s_nop 0
	v_cvt_pk_bf16_f32 v58, v48, v49
	v_pk_mul_f32 v[48:49], v[54:55], v[64:65] op_sel_hi:[1,0]
	s_nop 0
	v_exp_f32_e32 v48, v48
	v_exp_f32_e32 v49, v49
	s_nop 0
	v_pk_add_f32 v[48:49], v[48:49], 1.0 op_sel_hi:[1,0]
	s_nop 0
	v_rcp_f32_e32 v48, v48
	v_rcp_f32_e32 v49, v49
	s_nop 0
	v_pk_mul_f32 v[48:49], v[50:51], v[48:49]
	s_nop 0
	v_cvt_pk_bf16_f32 v59, v48, v49
	v_mad_i64_i32 v[48:49], s[36:37], v148, s74, v[142:143]
	global_store_dwordx4 v[48:49], v[56:59], off sc1
	v_fmamk_f32 v48, v147, 0x3a800000, v165
	v_rsq_f32_e32 v49, v48
	s_nop 0
	v_mul_f32_e32 v48, 0xbfb8aa3b, v49
	v_pk_mul_f32 v[52:53], v[44:45], v[48:49] op_sel_hi:[1,0]
	v_pk_mul_f32 v[44:45], v[46:47], v[48:49] op_sel_hi:[1,0]
	v_exp_f32_e32 v52, v52
	v_exp_f32_e32 v53, v53
	v_exp_f32_e32 v44, v44
	v_exp_f32_e32 v45, v45
	v_mul_f32_e32 v50, v49, v49
	v_pk_add_f32 v[52:53], v[52:53], 1.0 op_sel_hi:[1,0]
	v_pk_mul_f32 v[40:41], v[40:41], v[50:51] op_sel_hi:[1,0]
	v_pk_add_f32 v[44:45], v[44:45], 1.0 op_sel_hi:[1,0]
	v_rcp_f32_e32 v52, v52
	v_rcp_f32_e32 v53, v53
	v_rcp_f32_e32 v44, v44
	v_rcp_f32_e32 v45, v45
	v_pk_mul_f32 v[42:43], v[42:43], v[50:51] op_sel_hi:[1,0]
	v_pk_mul_f32 v[40:41], v[40:41], v[52:53]
	v_pk_mul_f32 v[32:33], v[32:33], v[50:51] op_sel_hi:[1,0]
	v_pk_mul_f32 v[42:43], v[42:43], v[44:45]
	v_cvt_pk_bf16_f32 v40, v40, v41
	v_pk_mul_f32 v[34:35], v[34:35], v[50:51] op_sel_hi:[1,0]
	v_cvt_pk_bf16_f32 v41, v42, v43
	v_pk_mul_f32 v[42:43], v[36:37], v[48:49] op_sel_hi:[1,0]
	s_nop 0
	v_exp_f32_e32 v42, v42
	v_exp_f32_e32 v43, v43
	s_nop 0
	v_pk_add_f32 v[42:43], v[42:43], 1.0 op_sel_hi:[1,0]
	s_nop 0
	v_rcp_f32_e32 v42, v42
	v_rcp_f32_e32 v43, v43
	s_nop 0
	v_pk_mul_f32 v[32:33], v[32:33], v[42:43]
	s_nop 0
	v_cvt_pk_bf16_f32 v42, v32, v33
	v_pk_mul_f32 v[32:33], v[38:39], v[48:49] op_sel_hi:[1,0]
	s_nop 0
	v_exp_f32_e32 v32, v32
	v_exp_f32_e32 v33, v33
	s_nop 0
	v_pk_add_f32 v[32:33], v[32:33], 1.0 op_sel_hi:[1,0]
	s_nop 0
	v_rcp_f32_e32 v32, v32
	v_rcp_f32_e32 v33, v33
	s_nop 0
	v_pk_mul_f32 v[32:33], v[34:35], v[32:33]
	s_nop 0
	v_cvt_pk_bf16_f32 v43, v32, v33
	v_mad_i64_i32 v[32:33], s[36:37], v146, s74, v[142:143]
	global_store_dwordx4 v[32:33], v[40:43], off sc1
	v_fmamk_f32 v32, v145, 0x3a800000, v165
	v_rsq_f32_e32 v33, v32
	s_nop 0
	v_mul_f32_e32 v32, 0xbfb8aa3b, v33
	v_pk_mul_f32 v[36:37], v[28:29], v[32:33] op_sel_hi:[1,0]
	v_pk_mul_f32 v[28:29], v[30:31], v[32:33] op_sel_hi:[1,0]
	v_exp_f32_e32 v36, v36
	v_exp_f32_e32 v37, v37
	v_exp_f32_e32 v28, v28
	v_exp_f32_e32 v29, v29
	v_mul_f32_e32 v34, v33, v33
	v_pk_add_f32 v[36:37], v[36:37], 1.0 op_sel_hi:[1,0]
	v_pk_mul_f32 v[24:25], v[24:25], v[34:35] op_sel_hi:[1,0]
	v_pk_add_f32 v[28:29], v[28:29], 1.0 op_sel_hi:[1,0]
	v_rcp_f32_e32 v36, v36
	v_rcp_f32_e32 v37, v37
	v_rcp_f32_e32 v28, v28
	v_rcp_f32_e32 v29, v29
	v_pk_mul_f32 v[26:27], v[26:27], v[34:35] op_sel_hi:[1,0]
	v_pk_mul_f32 v[24:25], v[24:25], v[36:37]
	v_pk_mul_f32 v[16:17], v[16:17], v[34:35] op_sel_hi:[1,0]
	v_pk_mul_f32 v[26:27], v[26:27], v[28:29]
	v_cvt_pk_bf16_f32 v24, v24, v25
	v_pk_mul_f32 v[18:19], v[18:19], v[34:35] op_sel_hi:[1,0]
	v_cvt_pk_bf16_f32 v25, v26, v27
	v_pk_mul_f32 v[26:27], v[20:21], v[32:33] op_sel_hi:[1,0]
	s_nop 0
	v_exp_f32_e32 v26, v26
	v_exp_f32_e32 v27, v27
	s_nop 0
	v_pk_add_f32 v[26:27], v[26:27], 1.0 op_sel_hi:[1,0]
	s_nop 0
	v_rcp_f32_e32 v26, v26
	v_rcp_f32_e32 v27, v27
	s_nop 0
	v_pk_mul_f32 v[16:17], v[16:17], v[26:27]
	s_nop 0
	v_cvt_pk_bf16_f32 v26, v16, v17
	v_pk_mul_f32 v[16:17], v[22:23], v[32:33] op_sel_hi:[1,0]
	s_nop 0
	v_exp_f32_e32 v16, v16
	v_exp_f32_e32 v17, v17
	s_nop 0
	v_pk_add_f32 v[16:17], v[16:17], 1.0 op_sel_hi:[1,0]
	s_nop 0
	v_rcp_f32_e32 v16, v16
	v_rcp_f32_e32 v17, v17
	s_nop 0
	v_pk_mul_f32 v[16:17], v[18:19], v[16:17]
	s_nop 0
	v_cvt_pk_bf16_f32 v27, v16, v17
	v_mad_i64_i32 v[16:17], s[36:37], v144, s74, v[142:143]
	global_store_dwordx4 v[16:17], v[24:27], off sc1
	v_fmamk_f32 v16, v141, 0x3a800000, v165
	v_rsq_f32_e32 v17, v16
	s_nop 0
	v_mul_f32_e32 v16, 0xbfb8aa3b, v17
	v_pk_mul_f32 v[20:21], v[12:13], v[16:17] op_sel_hi:[1,0]
	v_pk_mul_f32 v[12:13], v[14:15], v[16:17] op_sel_hi:[1,0]
	v_exp_f32_e32 v20, v20
	v_exp_f32_e32 v21, v21
	v_exp_f32_e32 v12, v12
	v_exp_f32_e32 v13, v13
	v_mul_f32_e32 v18, v17, v17
	v_pk_add_f32 v[20:21], v[20:21], 1.0 op_sel_hi:[1,0]
	v_pk_mul_f32 v[8:9], v[8:9], v[18:19] op_sel_hi:[1,0]
	v_pk_add_f32 v[12:13], v[12:13], 1.0 op_sel_hi:[1,0]
	v_rcp_f32_e32 v20, v20
	v_rcp_f32_e32 v21, v21
	v_rcp_f32_e32 v12, v12
	v_rcp_f32_e32 v13, v13
	v_pk_mul_f32 v[10:11], v[10:11], v[18:19] op_sel_hi:[1,0]
	v_pk_mul_f32 v[8:9], v[8:9], v[20:21]
	v_pk_mul_f32 v[0:1], v[0:1], v[18:19] op_sel_hi:[1,0]
	v_pk_mul_f32 v[10:11], v[10:11], v[12:13]
	v_cvt_pk_bf16_f32 v8, v8, v9
	v_pk_mul_f32 v[2:3], v[2:3], v[18:19] op_sel_hi:[1,0]
	v_cvt_pk_bf16_f32 v9, v10, v11
	v_pk_mul_f32 v[10:11], v[4:5], v[16:17] op_sel_hi:[1,0]
	s_nop 0
	v_exp_f32_e32 v10, v10
	v_exp_f32_e32 v11, v11
	s_nop 0
	v_pk_add_f32 v[10:11], v[10:11], 1.0 op_sel_hi:[1,0]
	s_nop 0
	v_rcp_f32_e32 v10, v10
	v_rcp_f32_e32 v11, v11
	s_nop 0
	v_pk_mul_f32 v[0:1], v[0:1], v[10:11]
	s_nop 0
	v_cvt_pk_bf16_f32 v10, v0, v1
	v_pk_mul_f32 v[0:1], v[6:7], v[16:17] op_sel_hi:[1,0]
	s_nop 0
	v_exp_f32_e32 v0, v0
	v_exp_f32_e32 v1, v1
	s_nop 0
	v_pk_add_f32 v[0:1], v[0:1], 1.0 op_sel_hi:[1,0]
	s_nop 0
	v_rcp_f32_e32 v0, v0
	v_rcp_f32_e32 v1, v1
	s_nop 0
	v_pk_mul_f32 v[0:1], v[2:3], v[0:1]
	s_nop 0
	v_cvt_pk_bf16_f32 v11, v0, v1
	v_mad_i64_i32 v[0:1], s[36:37], v140, s74, v[142:143]
	global_store_dwordx4 v[0:1], v[8:11], off sc1
	s_cbranch_vccnz .LBB0_602
	s_andn2_b64 vcc, exec, s[10:11]
	s_cbranch_vccnz .LBB0_601
	s_barrier
	s_branch .LBB0_601

; __device__ __forceinline__ unsigned cvt_pk(float lo, float hi) { unsigned r; asm("v_cvt_pk_bf16_f32 %0, %1, %2" : "=v"(r) : "v"(lo), "v"(hi)); return r; }
; __device__ __forceinline__ float fexp2(float x) { return __builtin_amdgcn_exp2f(x); }
; __device__ __forceinline__ float frcp(float x) { return __builtin_amdgcn_rcpf(x); }
;     __device__ __forceinline__ void operator()(AccRef acc, const pg8::Unit& u, int wr, int wc, int, int) const {
;     ...
;         bf16* ACT = (bf16*)(ws + WS_ACT); const float* ssq = (const float*)(ws + WS_SSQ) + ssq_off;
;         float sq[2][4];
; #pragma unroll
;         for (int ai = 0; ai < 2; ++ai)
; #pragma unroll
;             for (int m = 0; m < 4; ++m) sq[ai][m] = ssq[u.pm * 256 + ai * 128 + wr * 64 + m * 16 + fr];
;         asm volatile("" ::: "memory");
; #pragma unroll
;         for (int ai = 0; ai < 2; ++ai)
; #pragma unroll
;             for (int m = 0; m < 4; ++m) {
;                 const int row = u.pm * 256 + ai * 128 + wr * 64 + m * 16 + fr;
;                 const float rstd = __builtin_amdgcn_rsqf(sq[ai][m] * (1.0f / DM) + EPS);
;                 const float rc = -rstd * LOG2E, r2 = rstd * rstd;
;                 unsigned pk[4];
; #pragma unroll
;                 for (int n = 0; n < 2; ++n)
; #pragma unroll
;                     for (int h = 0; h < 2; ++h) {
;                         const f32x2 g2 = {acc[ai][0][m][n][2 * h], acc[ai][0][m][n][2 * h + 1]}, u2 = {acc[ai][1][m][n][2 * h], acc[ai][1][m][n][2 * h + 1]};
;                         const f32x2 x2 = g2 * rc; f32x2 d2; d2.x = fexp2(x2.x); d2.y = fexp2(x2.y); d2 = d2 + 1.0f;
;                         f32x2 q2; q2.x = frcp(d2.x); q2.y = frcp(d2.y);
;                         const f32x2 t2 = (g2 * u2) * r2 * q2;
;                         pk[2 * n + h] = cvt_pk(t2.x, t2.y);
;                     }
;                 v4u w; w.x = pk[0]; w.y = pk[1]; w.z = pk[2]; w.w = pk[3];
;                 *(v4u*)(ACT + (size_t)row * FF + u.pn * 128 + wc * 32 + 8 * fq) = w;
.LBB0_1249:
	s_mov_b64 s[44:45], s[20:21]
	s_mov_b64 s[42:43], s[22:23]
	s_add_u32 s42, s44, 0x64000
	s_addc_u32 s43, s45, 0
	s_lshl_b32 s15, s38, 8
	v_mov_b32_e32 v142, v196
	s_add_i32 s15, s15, s35
	v_pk_mul_f32 v[162:163], v[112:113], v[120:121]
	v_and_or_b32 v154, v142, 15, s15
	v_ashrrev_i32_e32 v155, 31, v154
	v_lshl_add_u64 v[140:141], v[154:155], 2, s[42:43]
	global_load_dword v155, v[140:141], off
	v_or_b32_e32 v144, 16, v154
	v_ashrrev_i32_e32 v145, 31, v144
	v_lshl_add_u64 v[140:141], v[144:145], 2, s[42:43]
	global_load_dword v145, v[140:141], off
	v_ashrrev_i32_e32 v120, 1, v142
	v_or_b32_e32 v146, 32, v154
	v_pk_mul_f32 v[156:157], v[118:119], v[126:127]
	v_pk_mul_f32 v[158:159], v[116:117], v[124:125]
	v_pk_mul_f32 v[160:161], v[114:115], v[122:123]
	v_and_b32_e32 v122, -8, v120
	v_or_b32_e32 v142, 48, v154
	v_add_u32_e32 v140, 0x80, v154
	v_add_u32_e32 v126, 0x90, v154
	v_add_u32_e32 v124, 0xa0, v154
	v_add_u32_e32 v120, 0xb0, v154
	v_ashrrev_i32_e32 v147, 31, v146
	v_ashrrev_i32_e32 v143, 31, v142
	v_ashrrev_i32_e32 v141, 31, v140
	v_ashrrev_i32_e32 v127, 31, v126
	v_ashrrev_i32_e32 v125, 31, v124
	v_ashrrev_i32_e32 v121, 31, v120
	v_lshl_add_u64 v[164:165], v[146:147], 2, s[42:43]
	v_lshl_add_u64 v[166:167], v[142:143], 2, s[42:43]
	v_lshl_add_u64 v[168:169], v[140:141], 2, s[42:43]
	v_lshl_add_u64 v[170:171], v[126:127], 2, s[42:43]
	v_lshl_add_u64 v[172:173], v[124:125], 2, s[42:43]
	v_lshl_add_u64 v[174:175], v[120:121], 2, s[42:43]
	global_load_dword v127, v[164:165], off
	global_load_dword v141, v[166:167], off
	global_load_dword v143, v[168:169], off
	global_load_dword v147, v[170:171], off
	global_load_dword v125, v[172:173], off
	global_load_dword v121, v[174:175], off
	s_lshl_b32 s46, s36, 7
	s_ashr_i32 s47, s46, 31
	s_lshl_b64 s[46:47], s[46:47], 1
	s_add_u32 s15, s44, s46
	s_addc_u32 s17, s45, s47
	s_add_u32 s42, s15, s53
	v_pk_mul_f32 v[104:105], v[108:109], v[104:105]
	v_ashrrev_i32_e32 v123, 31, v122
	s_addc_u32 s43, s17, 0
	v_lshl_add_u64 v[122:123], v[122:123], 1, s[42:43]
	v_lshl_add_u64 v[122:123], v[122:123], 0, s[12:13]
	v_pk_mul_f32 v[106:107], v[110:111], v[106:107]
	v_pk_mul_f32 v[96:97], v[100:101], v[96:97]
	v_pk_mul_f32 v[98:99], v[102:103], v[98:99]
	v_pk_mul_f32 v[88:89], v[92:93], v[88:89]
	v_pk_mul_f32 v[90:91], v[94:95], v[90:91]
	v_pk_mul_f32 v[80:81], v[84:85], v[80:81]
	v_pk_mul_f32 v[82:83], v[86:87], v[82:83]
	v_pk_mul_f32 v[72:73], v[76:77], v[72:73]
	v_pk_mul_f32 v[74:75], v[78:79], v[74:75]
	v_pk_mul_f32 v[64:65], v[68:69], v[64:65]
	v_pk_mul_f32 v[66:67], v[70:71], v[66:67]
	v_pk_mul_f32 v[56:57], v[60:61], v[56:57]
	v_pk_mul_f32 v[58:59], v[62:63], v[58:59]
	v_pk_mul_f32 v[48:49], v[52:53], v[48:49]
	v_pk_mul_f32 v[50:51], v[54:55], v[50:51]
	v_pk_mul_f32 v[40:41], v[44:45], v[40:41]
	v_pk_mul_f32 v[42:43], v[46:47], v[42:43]
	v_pk_mul_f32 v[32:33], v[36:37], v[32:33]
	v_pk_mul_f32 v[34:35], v[38:39], v[34:35]
	v_pk_mul_f32 v[24:25], v[28:29], v[24:25]
	v_pk_mul_f32 v[26:27], v[30:31], v[26:27]
	v_pk_mul_f32 v[16:17], v[20:21], v[16:17]
	v_pk_mul_f32 v[18:19], v[22:23], v[18:19]
	v_pk_mul_f32 v[8:9], v[12:13], v[8:9]
	v_pk_mul_f32 v[10:11], v[14:15], v[10:11]
	v_pk_mul_f32 v[0:1], v[4:5], v[0:1]
	v_pk_mul_f32 v[2:3], v[6:7], v[2:3]
	s_andn2_b64 vcc, exec, s[24:25]
	s_mov_b64 s[24:25], -1
	s_waitcnt vmcnt(0)
	v_fmamk_f32 v155, v155, 0x3a800000, v153
	v_rsq_f32_e32 v165, v155
	v_mad_i64_i32 v[154:155], s[42:43], v154, s54, v[122:123]
	v_fmamk_f32 v145, v145, 0x3a800000, v153
	v_mul_f32_e32 v164, 0xbfb8aa3b, v165
	v_pk_mul_f32 v[116:117], v[116:117], v[164:165] op_sel_hi:[1,0]
	v_pk_mul_f32 v[118:119], v[118:119], v[164:165] op_sel_hi:[1,0]
	v_pk_mul_f32 v[112:113], v[112:113], v[164:165] op_sel_hi:[1,0]
	v_pk_mul_f32 v[114:115], v[114:115], v[164:165] op_sel_hi:[1,0]
	v_rsq_f32_e32 v145, v145
	v_exp_f32_e32 v116, v116
	v_exp_f32_e32 v117, v117
	v_exp_f32_e32 v118, v118
	v_exp_f32_e32 v119, v119
	v_exp_f32_e32 v112, v112
	v_exp_f32_e32 v113, v113
	v_exp_f32_e32 v114, v114
	v_exp_f32_e32 v115, v115
	v_mul_f32_e32 v166, v165, v165
	v_mul_f32_e32 v164, 0xbfb8aa3b, v145
	v_pk_add_f32 v[116:117], v[116:117], 1.0 op_sel_hi:[1,0]
	v_pk_add_f32 v[118:119], v[118:119], 1.0 op_sel_hi:[1,0]
	v_pk_add_f32 v[112:113], v[112:113], 1.0 op_sel_hi:[1,0]
	v_pk_add_f32 v[114:115], v[114:115], 1.0 op_sel_hi:[1,0]
	v_pk_mul_f32 v[158:159], v[158:159], v[166:167] op_sel_hi:[1,0]
	v_pk_mul_f32 v[156:157], v[156:157], v[166:167] op_sel_hi:[1,0]
	v_pk_mul_f32 v[162:163], v[162:163], v[166:167] op_sel_hi:[1,0]
	v_pk_mul_f32 v[160:161], v[160:161], v[166:167] op_sel_hi:[1,0]
	v_pk_mul_f32 v[166:167], v[108:109], v[164:165] op_sel_hi:[1,0]
	v_rcp_f32_e32 v116, v116
	v_rcp_f32_e32 v117, v117
	v_rcp_f32_e32 v118, v118
	v_rcp_f32_e32 v119, v119
	v_rcp_f32_e32 v112, v112
	v_rcp_f32_e32 v113, v113
	v_rcp_f32_e32 v114, v114
	v_rcp_f32_e32 v115, v115
	v_pk_mul_f32 v[108:109], v[110:111], v[164:165] op_sel_hi:[1,0]
	v_exp_f32_e32 v166, v166
	v_exp_f32_e32 v167, v167
	v_exp_f32_e32 v108, v108
	v_exp_f32_e32 v109, v109
	v_pk_mul_f32 v[116:117], v[158:159], v[116:117]
	v_pk_mul_f32 v[118:119], v[156:157], v[118:119]
	v_pk_mul_f32 v[156:157], v[162:163], v[112:113]
	v_pk_mul_f32 v[158:159], v[160:161], v[114:115]
	v_cvt_pk_bf16_f32 v114, v156, v157
	v_cvt_pk_bf16_f32 v112, v116, v117
	v_cvt_pk_bf16_f32 v113, v118, v119
	v_pk_add_f32 v[108:109], v[108:109], 1.0 op_sel_hi:[1,0]
	v_cvt_pk_bf16_f32 v115, v158, v159
	global_store_dwordx4 v[154:155], v[112:115], off sc1
	v_rcp_f32_e32 v108, v108
	v_rcp_f32_e32 v109, v109
	v_pk_add_f32 v[114:115], v[166:167], 1.0 op_sel_hi:[1,0]
	v_pk_mul_f32 v[110:111], v[100:101], v[164:165] op_sel_hi:[1,0]
; __device__ __forceinline__ unsigned cvt_pk(float lo, float hi) { unsigned r; asm("v_cvt_pk_bf16_f32 %0, %1, %2" : "=v"(r) : "v"(lo), "v"(hi)); return r; }
; __device__ __forceinline__ float fexp2(float x) { return __builtin_amdgcn_exp2f(x); }
; __device__ __forceinline__ float frcp(float x) { return __builtin_amdgcn_rcpf(x); }
;     __device__ __forceinline__ void operator()(AccRef acc, const pg8::Unit& u, int wr, int wc, int, int) const {
;     ...
;         for (int ai = 0; ai < 2; ++ai)
; #pragma unroll
;             for (int m = 0; m < 4; ++m) {
;                 const int row = u.pm * 256 + ai * 128 + wr * 64 + m * 16 + fr;
;                 const float rstd = __builtin_amdgcn_rsqf(sq[ai][m] * (1.0f / DM) + EPS);
;                 const float rc = -rstd * LOG2E, r2 = rstd * rstd;
;                 unsigned pk[4];
; #pragma unroll
;                 for (int n = 0; n < 2; ++n)
; #pragma unroll
;                     for (int h = 0; h < 2; ++h) {
;                         const f32x2 g2 = {acc[ai][0][m][n][2 * h], acc[ai][0][m][n][2 * h + 1]}, u2 = {acc[ai][1][m][n][2 * h], acc[ai][1][m][n][2 * h + 1]};
;                         const f32x2 x2 = g2 * rc; f32x2 d2; d2.x = fexp2(x2.x); d2.y = fexp2(x2.y); d2 = d2 + 1.0f;
;                         f32x2 q2; q2.x = frcp(d2.x); q2.y = frcp(d2.y);
;                         const f32x2 t2 = (g2 * u2) * r2 * q2;
;                         pk[2 * n + h] = cvt_pk(t2.x, t2.y);
;                     }
;                 v4u w; w.x = pk[0]; w.y = pk[1]; w.z = pk[2]; w.w = pk[3];
;                 *(v4u*)(ACT + (size_t)row * FF + u.pn * 128 + wc * 32 + 8 * fq) = w;
	v_rcp_f32_e32 v114, v114
	v_rcp_f32_e32 v115, v115
	v_exp_f32_e32 v110, v110
	v_exp_f32_e32 v111, v111
	v_mul_f32_e32 v112, v145, v145
	v_pk_mul_f32 v[104:105], v[104:105], v[112:113] op_sel_hi:[1,0]
	v_pk_mul_f32 v[106:107], v[106:107], v[112:113] op_sel_hi:[1,0]
	v_pk_mul_f32 v[104:105], v[104:105], v[114:115]
	v_pk_mul_f32 v[106:107], v[106:107], v[108:109]
	v_cvt_pk_bf16_f32 v104, v104, v105
	v_pk_mul_f32 v[100:101], v[102:103], v[164:165] op_sel_hi:[1,0]
	v_cvt_pk_bf16_f32 v105, v106, v107
	v_pk_add_f32 v[106:107], v[110:111], 1.0 op_sel_hi:[1,0]
	v_exp_f32_e32 v100, v100
	v_rcp_f32_e32 v106, v106
	v_rcp_f32_e32 v107, v107
	v_exp_f32_e32 v101, v101
	v_pk_mul_f32 v[96:97], v[96:97], v[112:113] op_sel_hi:[1,0]
	v_pk_mul_f32 v[98:99], v[98:99], v[112:113] op_sel_hi:[1,0]
	v_pk_mul_f32 v[96:97], v[96:97], v[106:107]
	s_nop 0
	v_cvt_pk_bf16_f32 v106, v96, v97
	v_pk_add_f32 v[96:97], v[100:101], 1.0 op_sel_hi:[1,0]
	v_fmamk_f32 v100, v127, 0x3a800000, v153
	v_rcp_f32_e32 v96, v96
	v_rcp_f32_e32 v97, v97
	v_rsq_f32_e32 v102, v100
	v_mad_i64_i32 v[100:101], s[42:43], v144, s54, v[122:123]
	v_pk_mul_f32 v[96:97], v[98:99], v[96:97]
	s_nop 0
	v_cvt_pk_bf16_f32 v107, v96, v97
	v_mul_f32_e32 v96, 0xbfb8aa3b, v102
	v_pk_mul_f32 v[98:99], v[92:93], v[96:97] op_sel_hi:[1,0]
	v_pk_mul_f32 v[92:93], v[94:95], v[96:97] op_sel_hi:[1,0]
	v_exp_f32_e32 v98, v98
	v_exp_f32_e32 v99, v99
	v_exp_f32_e32 v92, v92
	v_exp_f32_e32 v93, v93
	v_pk_mul_f32 v[94:95], v[84:85], v[96:97] op_sel_hi:[1,0]
	v_pk_add_f32 v[98:99], v[98:99], 1.0 op_sel_hi:[1,0]
	v_exp_f32_e32 v94, v94
	v_pk_add_f32 v[92:93], v[92:93], 1.0 op_sel_hi:[1,0]
	v_rcp_f32_e32 v98, v98
	v_rcp_f32_e32 v99, v99
	v_rcp_f32_e32 v92, v92
	v_rcp_f32_e32 v93, v93
	v_exp_f32_e32 v95, v95
	global_store_dwordx4 v[100:101], v[104:107], off sc1
	v_mul_f32_e32 v100, v102, v102
	v_pk_mul_f32 v[88:89], v[88:89], v[100:101] op_sel_hi:[1,0]
	v_pk_mul_f32 v[90:91], v[90:91], v[100:101] op_sel_hi:[1,0]
	v_pk_mul_f32 v[88:89], v[88:89], v[98:99]
	v_pk_mul_f32 v[90:91], v[90:91], v[92:93]
	v_cvt_pk_bf16_f32 v88, v88, v89
	v_pk_mul_f32 v[84:85], v[86:87], v[96:97] op_sel_hi:[1,0]
	v_cvt_pk_bf16_f32 v89, v90, v91
	v_pk_add_f32 v[90:91], v[94:95], 1.0 op_sel_hi:[1,0]
	v_exp_f32_e32 v84, v84
	v_rcp_f32_e32 v90, v90
	v_rcp_f32_e32 v91, v91
	v_exp_f32_e32 v85, v85
	v_pk_mul_f32 v[80:81], v[80:81], v[100:101] op_sel_hi:[1,0]
	v_pk_mul_f32 v[82:83], v[82:83], v[100:101] op_sel_hi:[1,0]
	v_pk_mul_f32 v[80:81], v[80:81], v[90:91]
	s_nop 0
	v_cvt_pk_bf16_f32 v90, v80, v81
	v_pk_add_f32 v[80:81], v[84:85], 1.0 op_sel_hi:[1,0]
	v_fmamk_f32 v84, v141, 0x3a800000, v153
	v_rcp_f32_e32 v80, v80
	v_rcp_f32_e32 v81, v81
	v_rsq_f32_e32 v86, v84
	v_mad_i64_i32 v[84:85], s[42:43], v146, s54, v[122:123]
	v_pk_mul_f32 v[80:81], v[82:83], v[80:81]
	s_nop 0
	v_cvt_pk_bf16_f32 v91, v80, v81
	v_mul_f32_e32 v80, 0xbfb8aa3b, v86
	v_pk_mul_f32 v[82:83], v[76:77], v[80:81] op_sel_hi:[1,0]
	v_pk_mul_f32 v[76:77], v[78:79], v[80:81] op_sel_hi:[1,0]
	v_exp_f32_e32 v82, v82
	v_exp_f32_e32 v83, v83
	v_exp_f32_e32 v76, v76
	v_exp_f32_e32 v77, v77
	v_pk_mul_f32 v[78:79], v[68:69], v[80:81] op_sel_hi:[1,0]
	v_pk_add_f32 v[82:83], v[82:83], 1.0 op_sel_hi:[1,0]
	v_exp_f32_e32 v78, v78
	v_pk_add_f32 v[76:77], v[76:77], 1.0 op_sel_hi:[1,0]
	v_rcp_f32_e32 v82, v82
	v_rcp_f32_e32 v83, v83
	v_rcp_f32_e32 v76, v76
	v_rcp_f32_e32 v77, v77
	v_exp_f32_e32 v79, v79
	global_store_dwordx4 v[84:85], v[88:91], off sc1
	v_mul_f32_e32 v84, v86, v86
	v_pk_mul_f32 v[72:73], v[72:73], v[84:85] op_sel_hi:[1,0]
	v_pk_mul_f32 v[74:75], v[74:75], v[84:85] op_sel_hi:[1,0]
	v_pk_mul_f32 v[72:73], v[72:73], v[82:83]
	v_pk_mul_f32 v[74:75], v[74:75], v[76:77]
	v_cvt_pk_bf16_f32 v72, v72, v73
	v_pk_mul_f32 v[68:69], v[70:71], v[80:81] op_sel_hi:[1,0]
	v_cvt_pk_bf16_f32 v73, v74, v75
	v_pk_add_f32 v[74:75], v[78:79], 1.0 op_sel_hi:[1,0]
	v_exp_f32_e32 v68, v68
	v_rcp_f32_e32 v74, v74
	v_rcp_f32_e32 v75, v75
	v_exp_f32_e32 v69, v69
	v_pk_mul_f32 v[64:65], v[64:65], v[84:85] op_sel_hi:[1,0]
	v_pk_mul_f32 v[66:67], v[66:67], v[84:85] op_sel_hi:[1,0]
	v_pk_mul_f32 v[64:65], v[64:65], v[74:75]
	s_nop 0
	v_cvt_pk_bf16_f32 v74, v64, v65
	v_pk_add_f32 v[64:65], v[68:69], 1.0 op_sel_hi:[1,0]
	v_fmamk_f32 v68, v143, 0x3a800000, v153
	v_rcp_f32_e32 v64, v64
	v_rcp_f32_e32 v65, v65
	v_rsq_f32_e32 v70, v68
	v_mad_i64_i32 v[68:69], s[42:43], v142, s54, v[122:123]
	v_pk_mul_f32 v[64:65], v[66:67], v[64:65]
	s_nop 0
	v_cvt_pk_bf16_f32 v75, v64, v65
	v_mul_f32_e32 v64, 0xbfb8aa3b, v70
	v_pk_mul_f32 v[66:67], v[60:61], v[64:65] op_sel_hi:[1,0]
	v_pk_mul_f32 v[60:61], v[62:63], v[64:65] op_sel_hi:[1,0]
	v_exp_f32_e32 v66, v66
	v_exp_f32_e32 v67, v67
	v_exp_f32_e32 v60, v60
	v_exp_f32_e32 v61, v61
	v_pk_mul_f32 v[62:63], v[52:53], v[64:65] op_sel_hi:[1,0]
	v_pk_add_f32 v[66:67], v[66:67], 1.0 op_sel_hi:[1,0]
	v_exp_f32_e32 v62, v62
	v_pk_add_f32 v[60:61], v[60:61], 1.0 op_sel_hi:[1,0]
	v_rcp_f32_e32 v66, v66
	v_rcp_f32_e32 v67, v67
	v_rcp_f32_e32 v60, v60
	v_rcp_f32_e32 v61, v61
	v_exp_f32_e32 v63, v63
	global_store_dwordx4 v[68:69], v[72:75], off sc1
	v_mul_f32_e32 v68, v70, v70
	v_pk_mul_f32 v[56:57], v[56:57], v[68:69] op_sel_hi:[1,0]
	v_pk_mul_f32 v[58:59], v[58:59], v[68:69] op_sel_hi:[1,0]
	v_pk_mul_f32 v[56:57], v[56:57], v[66:67]
	v_pk_mul_f32 v[58:59], v[58:59], v[60:61]
	v_cvt_pk_bf16_f32 v56, v56, v57
	v_pk_mul_f32 v[52:53], v[54:55], v[64:65] op_sel_hi:[1,0]
	v_cvt_pk_bf16_f32 v57, v58, v59
	v_pk_add_f32 v[58:59], v[62:63], 1.0 op_sel_hi:[1,0]
	v_exp_f32_e32 v52, v52
	v_rcp_f32_e32 v58, v58
; __device__ __forceinline__ unsigned cvt_pk(float lo, float hi) { unsigned r; asm("v_cvt_pk_bf16_f32 %0, %1, %2" : "=v"(r) : "v"(lo), "v"(hi)); return r; }
; __device__ __forceinline__ float fexp2(float x) { return __builtin_amdgcn_exp2f(x); }
; __device__ __forceinline__ float frcp(float x) { return __builtin_amdgcn_rcpf(x); }
;     __device__ __forceinline__ void operator()(AccRef acc, const pg8::Unit& u, int wr, int wc, int, int) const {
;     ...
;         for (int ai = 0; ai < 2; ++ai)
; #pragma unroll
;             for (int m = 0; m < 4; ++m) {
;                 const int row = u.pm * 256 + ai * 128 + wr * 64 + m * 16 + fr;
;                 const float rstd = __builtin_amdgcn_rsqf(sq[ai][m] * (1.0f / DM) + EPS);
;                 const float rc = -rstd * LOG2E, r2 = rstd * rstd;
;                 unsigned pk[4];
; #pragma unroll
;                 for (int n = 0; n < 2; ++n)
; #pragma unroll
;                     for (int h = 0; h < 2; ++h) {
;                         const f32x2 g2 = {acc[ai][0][m][n][2 * h], acc[ai][0][m][n][2 * h + 1]}, u2 = {acc[ai][1][m][n][2 * h], acc[ai][1][m][n][2 * h + 1]};
;                         const f32x2 x2 = g2 * rc; f32x2 d2; d2.x = fexp2(x2.x); d2.y = fexp2(x2.y); d2 = d2 + 1.0f;
;                         f32x2 q2; q2.x = frcp(d2.x); q2.y = frcp(d2.y);
;                         const f32x2 t2 = (g2 * u2) * r2 * q2;
;                         pk[2 * n + h] = cvt_pk(t2.x, t2.y);
;                     }
;                 v4u w; w.x = pk[0]; w.y = pk[1]; w.z = pk[2]; w.w = pk[3];
;                 *(v4u*)(ACT + (size_t)row * FF + u.pn * 128 + wc * 32 + 8 * fq) = w;
	v_rcp_f32_e32 v59, v59
	v_exp_f32_e32 v53, v53
	v_pk_mul_f32 v[48:49], v[48:49], v[68:69] op_sel_hi:[1,0]
	v_pk_mul_f32 v[50:51], v[50:51], v[68:69] op_sel_hi:[1,0]
	v_pk_mul_f32 v[48:49], v[48:49], v[58:59]
	s_nop 0
	v_cvt_pk_bf16_f32 v58, v48, v49
	v_pk_add_f32 v[48:49], v[52:53], 1.0 op_sel_hi:[1,0]
	v_fmamk_f32 v52, v147, 0x3a800000, v153
	v_rcp_f32_e32 v48, v48
	v_rcp_f32_e32 v49, v49
	v_rsq_f32_e32 v54, v52
	v_mad_i64_i32 v[52:53], s[42:43], v140, s54, v[122:123]
	v_pk_mul_f32 v[48:49], v[50:51], v[48:49]
	s_nop 0
	v_cvt_pk_bf16_f32 v59, v48, v49
	v_mul_f32_e32 v48, 0xbfb8aa3b, v54
	v_pk_mul_f32 v[50:51], v[44:45], v[48:49] op_sel_hi:[1,0]
	v_pk_mul_f32 v[44:45], v[46:47], v[48:49] op_sel_hi:[1,0]
	v_exp_f32_e32 v50, v50
	v_exp_f32_e32 v51, v51
	v_exp_f32_e32 v44, v44
	v_exp_f32_e32 v45, v45
	v_pk_mul_f32 v[46:47], v[36:37], v[48:49] op_sel_hi:[1,0]
	v_pk_add_f32 v[50:51], v[50:51], 1.0 op_sel_hi:[1,0]
	v_exp_f32_e32 v46, v46
	v_pk_add_f32 v[44:45], v[44:45], 1.0 op_sel_hi:[1,0]
	v_rcp_f32_e32 v50, v50
	v_rcp_f32_e32 v51, v51
	v_rcp_f32_e32 v44, v44
	v_rcp_f32_e32 v45, v45
	v_exp_f32_e32 v47, v47
	global_store_dwordx4 v[52:53], v[56:59], off sc1
	v_mul_f32_e32 v52, v54, v54
	v_pk_mul_f32 v[40:41], v[40:41], v[52:53] op_sel_hi:[1,0]
	v_pk_mul_f32 v[42:43], v[42:43], v[52:53] op_sel_hi:[1,0]
	v_pk_mul_f32 v[40:41], v[40:41], v[50:51]
	v_pk_mul_f32 v[42:43], v[42:43], v[44:45]
	v_cvt_pk_bf16_f32 v40, v40, v41
	v_pk_mul_f32 v[36:37], v[38:39], v[48:49] op_sel_hi:[1,0]
	v_cvt_pk_bf16_f32 v41, v42, v43
	v_pk_add_f32 v[42:43], v[46:47], 1.0 op_sel_hi:[1,0]
	v_exp_f32_e32 v36, v36
	v_rcp_f32_e32 v42, v42
	v_rcp_f32_e32 v43, v43
	v_exp_f32_e32 v37, v37
	v_pk_mul_f32 v[32:33], v[32:33], v[52:53] op_sel_hi:[1,0]
	v_pk_mul_f32 v[34:35], v[34:35], v[52:53] op_sel_hi:[1,0]
	v_pk_mul_f32 v[32:33], v[32:33], v[42:43]
	s_nop 0
	v_cvt_pk_bf16_f32 v42, v32, v33
	v_pk_add_f32 v[32:33], v[36:37], 1.0 op_sel_hi:[1,0]
	v_fmamk_f32 v36, v125, 0x3a800000, v153
	v_rcp_f32_e32 v32, v32
	v_rcp_f32_e32 v33, v33
	v_rsq_f32_e32 v38, v36
	v_mad_i64_i32 v[36:37], s[42:43], v126, s54, v[122:123]
	v_pk_mul_f32 v[32:33], v[34:35], v[32:33]
	s_nop 0
	v_cvt_pk_bf16_f32 v43, v32, v33
	v_mul_f32_e32 v32, 0xbfb8aa3b, v38
	v_pk_mul_f32 v[34:35], v[28:29], v[32:33] op_sel_hi:[1,0]
	v_pk_mul_f32 v[28:29], v[30:31], v[32:33] op_sel_hi:[1,0]
	v_exp_f32_e32 v34, v34
	v_exp_f32_e32 v35, v35
	v_exp_f32_e32 v28, v28
	v_exp_f32_e32 v29, v29
	v_pk_mul_f32 v[30:31], v[20:21], v[32:33] op_sel_hi:[1,0]
	v_pk_add_f32 v[34:35], v[34:35], 1.0 op_sel_hi:[1,0]
	v_exp_f32_e32 v30, v30
	v_pk_add_f32 v[28:29], v[28:29], 1.0 op_sel_hi:[1,0]
	v_rcp_f32_e32 v34, v34
	v_rcp_f32_e32 v35, v35
	v_rcp_f32_e32 v28, v28
	v_rcp_f32_e32 v29, v29
	v_exp_f32_e32 v31, v31
	global_store_dwordx4 v[36:37], v[40:43], off sc1
	v_mul_f32_e32 v36, v38, v38
	v_pk_mul_f32 v[24:25], v[24:25], v[36:37] op_sel_hi:[1,0]
	v_pk_mul_f32 v[26:27], v[26:27], v[36:37] op_sel_hi:[1,0]
	v_pk_mul_f32 v[24:25], v[24:25], v[34:35]
	v_pk_mul_f32 v[26:27], v[26:27], v[28:29]
	v_cvt_pk_bf16_f32 v24, v24, v25
	v_pk_mul_f32 v[20:21], v[22:23], v[32:33] op_sel_hi:[1,0]
	v_cvt_pk_bf16_f32 v25, v26, v27
	v_pk_add_f32 v[26:27], v[30:31], 1.0 op_sel_hi:[1,0]
	v_exp_f32_e32 v20, v20
	v_rcp_f32_e32 v26, v26
	v_rcp_f32_e32 v27, v27
	v_exp_f32_e32 v21, v21
	v_pk_mul_f32 v[16:17], v[16:17], v[36:37] op_sel_hi:[1,0]
	v_pk_mul_f32 v[18:19], v[18:19], v[36:37] op_sel_hi:[1,0]
	v_pk_mul_f32 v[16:17], v[16:17], v[26:27]
	s_nop 0
	v_cvt_pk_bf16_f32 v26, v16, v17
	v_pk_add_f32 v[16:17], v[20:21], 1.0 op_sel_hi:[1,0]
	v_fmamk_f32 v20, v121, 0x3a800000, v153
	v_rcp_f32_e32 v16, v16
	v_rcp_f32_e32 v17, v17
	v_rsq_f32_e32 v22, v20
	v_mad_i64_i32 v[20:21], s[42:43], v124, s54, v[122:123]
	v_pk_mul_f32 v[16:17], v[18:19], v[16:17]
	s_nop 0
	v_cvt_pk_bf16_f32 v27, v16, v17
	v_mul_f32_e32 v16, 0xbfb8aa3b, v22
	v_pk_mul_f32 v[18:19], v[12:13], v[16:17] op_sel_hi:[1,0]
	v_pk_mul_f32 v[12:13], v[14:15], v[16:17] op_sel_hi:[1,0]
	v_exp_f32_e32 v18, v18
	v_exp_f32_e32 v12, v12
	v_exp_f32_e32 v13, v13
	v_exp_f32_e32 v19, v19
	global_store_dwordx4 v[20:21], v[24:27], off sc1
	v_mul_f32_e32 v20, v22, v22
	v_pk_add_f32 v[12:13], v[12:13], 1.0 op_sel_hi:[1,0]
	v_pk_add_f32 v[18:19], v[18:19], 1.0 op_sel_hi:[1,0]
	v_rcp_f32_e32 v12, v12
	v_rcp_f32_e32 v13, v13
	v_rcp_f32_e32 v18, v18
	v_rcp_f32_e32 v19, v19
	v_pk_mul_f32 v[14:15], v[4:5], v[16:17] op_sel_hi:[1,0]
	v_pk_mul_f32 v[10:11], v[10:11], v[20:21] op_sel_hi:[1,0]
	v_exp_f32_e32 v14, v14
	v_exp_f32_e32 v15, v15
	v_pk_mul_f32 v[10:11], v[10:11], v[12:13]
	v_pk_mul_f32 v[12:13], v[6:7], v[16:17] op_sel_hi:[1,0]
	v_pk_mul_f32 v[8:9], v[8:9], v[20:21] op_sel_hi:[1,0]
	v_exp_f32_e32 v12, v12
	v_exp_f32_e32 v13, v13
	v_pk_mul_f32 v[8:9], v[8:9], v[18:19]
	v_pk_mul_f32 v[0:1], v[0:1], v[20:21] op_sel_hi:[1,0]
	v_cvt_pk_bf16_f32 v8, v8, v9
	v_cvt_pk_bf16_f32 v9, v10, v11
	v_pk_add_f32 v[10:11], v[14:15], 1.0 op_sel_hi:[1,0]
	v_pk_add_f32 v[4:5], v[12:13], 1.0 op_sel_hi:[1,0]
	v_rcp_f32_e32 v10, v10
	v_rcp_f32_e32 v11, v11
	v_rcp_f32_e32 v4, v4
	v_rcp_f32_e32 v5, v5
	v_pk_mul_f32 v[0:1], v[0:1], v[10:11]
	s_nop 0
	v_cvt_pk_bf16_f32 v10, v0, v1
	v_pk_mul_f32 v[0:1], v[2:3], v[20:21] op_sel_hi:[1,0]
	s_nop 0
	v_pk_mul_f32 v[0:1], v[0:1], v[4:5]
	s_nop 0
	v_cvt_pk_bf16_f32 v11, v0, v1
	v_mad_i64_i32 v[0:1], s[42:43], v120, s54, v[122:123]
	global_store_dwordx4 v[0:1], v[8:11], off sc1
	s_cbranch_vccnz .LBB0_1239
	s_andn2_b64 vcc, exec, s[8:9]
	s_cbranch_vccnz .LBB0_1238
	s_barrier
	s_branch .LBB0_1238
